# prep phase: K fragment copy items take their eight rows from one batch of loads, no per-row drain; V copy row loads issued together
# speedup vs baseline: 1.0052x; 1.0022x over previous
; DI void phase_prep(const Args& a, int layer, LAS unsigned char* lds) {
;     ...
;             if (which >= 3) {
;                 const int srccol = (which == 3 ? C_KS : which == 4 ? C_KW : C_KB) + g * 64;
;                 bf16_t* dst = (bf16_t*)(ws + (which == 3 ? WS_KSF : which == 4 ? WS_KWF : WS_KBF)) + (size_t)bg * 64 * S + (size_t)st * 4096;
;                 float rmax = 0.f;
; #pragma unroll
;                 for (int i = 0; i < 8; ++i) { const int tok = i * 8 + (lane >> 3), q = lane & 7;
;                     const u32x4 v = *(const u32x4*)(P + (size_t)(b * S + st * 64 + tok) * NP + srccol + q * 8);
;                     const int pos = which == 3 ? (((tok >> 4) * 2 + (q >> 2)) * 64 + (q & 3) * 16 + (tok & 15))
;                                                : ((tok >> 5) * 256 + (q >> 1) * 64 + (q & 1) * 32 + (tok & 31));
;                     *(u32x4*)(dst + pos * 8) = v;
;                     float ss = bflo(v.x) * bflo(v.x) + bfhi(v.x) * bfhi(v.x) + bflo(v.y) * bflo(v.y) + bfhi(v.y) * bfhi(v.y)
;                              + bflo(v.z) * bflo(v.z) + bfhi(v.z) * bfhi(v.z) + bflo(v.w) * bflo(v.w) + bfhi(v.w) * bfhi(v.w);
;                     ss += __shfl_xor(ss, 1); ss += __shfl_xor(ss, 2); ss += __shfl_xor(ss, 4);
;                     rmax = fmaxf(rmax, ss); }
.LBB0_349:
	s_andn2_saveexec_b64 s[42:43], s[42:43]
	s_cbranch_execz .LBB0_346
	v_and_b32_e32 v1, 0x7ffffc00, v52
	s_movk_i32 s0, 0xc00
	v_cmp_eq_u32_e64 s[38:39], s0, v1
	v_cmp_eq_u32_e64 s[0:1], s26, v1
	v_mov_b32_e32 v3, v129
	v_cndmask_b32_e64 v59, v21, v37, s[38:39]
	v_cndmask_b32_e64 v1, v208, v209, s[0:1]
	v_cndmask_b32_e64 v13, v1, v210, s[38:39]
	v_cndmask_b32_e64 v1, v211, v212, s[0:1]
	v_cndmask_b32_e64 v128, v1, v213, s[38:39]
	v_lshl_add_u64 v[10:11], s[98:99], 0, v[128:129]
	v_lshl_add_u64 v[2:3], v[10:11], 0, v[2:3]
	v_mov_b32_e32 v1, v129
	v_lshl_add_u64 v[10:11], v[2:3], 0, v[0:1]
	v_and_b32_e32 v3, 64, v197
	v_xor_b32_e32 v2, 1, v197
	v_add_u32_e32 v54, 64, v3
	v_cmp_lt_i32_e64 s[0:1], v2, v54
	v_lshlrev_b32_e32 v0, 1, v13
	v_lshl_or_b32 v128, v12, 7, v0
	v_cndmask_b32_e64 v2, v197, v2, s[0:1]
	v_lshlrev_b32_e32 v57, 2, v2
	v_xor_b32_e32 v2, 2, v197
	v_cmp_lt_i32_e64 s[0:1], v2, v54
	v_lshl_add_u64 v[0:1], v[6:7], 0, v[128:129]
	v_or_b32_e32 v68, v58, v17
	v_mul_u32_u24_e32 v68, 0xd00, v68
	v_lshlrev_b32_e32 v68, 1, v68
	v_mov_b32_e32 v69, v129
	v_lshl_add_u64 v[68:69], v[0:1], 0, v[68:69]
	global_load_dwordx4 v[70:73], v[68:69], off
	v_or_b32_e32 v68, v58, v22
	v_mul_u32_u24_e32 v68, 0xd00, v68
	v_lshlrev_b32_e32 v68, 1, v68
	v_mov_b32_e32 v69, v129
	v_lshl_add_u64 v[68:69], v[0:1], 0, v[68:69]
	global_load_dwordx4 v[74:77], v[68:69], off
	v_or_b32_e32 v68, v58, v23
	v_mul_u32_u24_e32 v68, 0xd00, v68
	v_lshlrev_b32_e32 v68, 1, v68
	v_mov_b32_e32 v69, v129
	v_lshl_add_u64 v[68:69], v[0:1], 0, v[68:69]
	global_load_dwordx4 v[78:81], v[68:69], off
	v_or_b32_e32 v68, v58, v24
	v_mul_u32_u24_e32 v68, 0xd00, v68
	v_lshlrev_b32_e32 v68, 1, v68
	v_mov_b32_e32 v69, v129
	v_lshl_add_u64 v[68:69], v[0:1], 0, v[68:69]
	global_load_dwordx4 v[82:85], v[68:69], off
	v_or_b32_e32 v68, v58, v25
	v_mul_u32_u24_e32 v68, 0xd00, v68
	v_lshlrev_b32_e32 v68, 1, v68
	v_mov_b32_e32 v69, v129
	v_lshl_add_u64 v[68:69], v[0:1], 0, v[68:69]
	global_load_dwordx4 v[86:89], v[68:69], off
	v_or_b32_e32 v68, v58, v26
	v_mul_u32_u24_e32 v68, 0xd00, v68
	v_lshlrev_b32_e32 v68, 1, v68
	v_mov_b32_e32 v69, v129
	v_lshl_add_u64 v[68:69], v[0:1], 0, v[68:69]
	global_load_dwordx4 v[90:93], v[68:69], off
	v_or_b32_e32 v68, v58, v27
	v_mul_u32_u24_e32 v68, 0xd00, v68
	v_lshlrev_b32_e32 v68, 1, v68
	v_mov_b32_e32 v69, v129
	v_lshl_add_u64 v[68:69], v[0:1], 0, v[68:69]
	global_load_dwordx4 v[94:97], v[68:69], off
	v_or_b32_e32 v68, v58, v28
	v_mul_u32_u24_e32 v68, 0xd00, v68
	v_lshlrev_b32_e32 v68, 1, v68
	v_mov_b32_e32 v69, v129
	v_lshl_add_u64 v[68:69], v[0:1], 0, v[68:69]
	global_load_dwordx4 v[98:101], v[68:69], off
	s_waitcnt vmcnt(0)
	v_or_b32_e32 v12, v59, v17
	v_cndmask_b32_e64 v2, v197, v2, s[0:1]
	v_lshlrev_b32_e32 v56, 2, v2
	v_xor_b32_e32 v2, 4, v197
	v_cmp_lt_i32_e64 s[0:1], v2, v54
	s_nop 1
	v_cndmask_b32_e64 v2, v197, v2, s[0:1]
	v_lshlrev_b32_e32 v55, 2, v2
	v_or_b32_e32 v2, v58, v17
	v_mul_u32_u24_e32 v2, 0xd00, v2
	v_lshlrev_b32_e32 v128, 1, v2
	v_lshl_add_u64 v[2:3], v[0:1], 0, v[128:129]
	v_mov_b64_e32 v[60:61], v[70:71]
	v_mov_b64_e32 v[62:63], v[72:73]
	v_lshlrev_b32_e32 v128, 4, v12
	v_lshl_add_u64 v[12:13], v[10:11], 0, v[128:129]
	s_mov_b32 s0, 0x34000
	v_add_co_u32_e64 v2, s[0:1], s0, v2
	global_store_dwordx4 v[12:13], v[60:63], off
	v_lshlrev_b32_e32 v64, 16, v60
	s_nop 0
	v_and_b32_e32 v60, 0xffff0000, v60
	v_mul_f32_e32 v60, v60, v60
	v_fmac_f32_e32 v60, v64, v64
	v_lshlrev_b32_e32 v64, 16, v61
	v_fmac_f32_e32 v60, v64, v64
	v_and_b32_e32 v61, 0xffff0000, v61
	v_fmac_f32_e32 v60, v61, v61
	v_lshlrev_b32_e32 v61, 16, v62
	v_fmac_f32_e32 v60, v61, v61
	v_and_b32_e32 v61, 0xffff0000, v62
	v_fmac_f32_e32 v60, v61, v61
	v_lshlrev_b32_e32 v61, 16, v63
	v_fmac_f32_e32 v60, v61, v61
	v_and_b32_e32 v61, 0xffff0000, v63
	v_fmac_f32_e32 v60, v61, v61
	ds_bpermute_b32 v61, v57, v60
	v_or_b32_e32 v64, v59, v22
	v_addc_co_u32_e64 v3, s[0:1], 0, v3, s[0:1]
	s_waitcnt lgkmcnt(0)
	v_add_f32_e32 v60, v60, v61
	ds_bpermute_b32 v61, v56, v60
	s_waitcnt lgkmcnt(0)
	v_add_f32_e32 v60, v60, v61
	ds_bpermute_b32 v61, v55, v60
	s_waitcnt lgkmcnt(0)
	v_add_f32_e32 v66, v60, v61
	v_or_b32_e32 v60, v58, v22
	v_mul_u32_u24_e32 v60, 0xd00, v60
	v_lshlrev_b32_e32 v128, 1, v60
	v_lshl_add_u64 v[60:61], v[0:1], 0, v[128:129]
	v_mov_b64_e32 v[60:61], v[74:75]
	v_mov_b64_e32 v[62:63], v[76:77]
	v_lshlrev_b32_e32 v128, 4, v64
	v_lshl_add_u64 v[64:65], v[10:11], 0, v[128:129]
	global_store_dwordx4 v[64:65], v[60:63], off
	v_lshlrev_b32_e32 v64, 16, v60
	s_nop 0
	v_and_b32_e32 v60, 0xffff0000, v60
	v_mul_f32_e32 v60, v60, v60
	v_fmac_f32_e32 v60, v64, v64
	v_lshlrev_b32_e32 v64, 16, v61
	v_fmac_f32_e32 v60, v64, v64
	v_and_b32_e32 v61, 0xffff0000, v61
	v_fmac_f32_e32 v60, v61, v61
	v_lshlrev_b32_e32 v61, 16, v62
	v_fmac_f32_e32 v60, v61, v61
	v_and_b32_e32 v61, 0xffff0000, v62
	v_fmac_f32_e32 v60, v61, v61
	v_lshlrev_b32_e32 v61, 16, v63
	v_fmac_f32_e32 v60, v61, v61
	v_and_b32_e32 v61, 0xffff0000, v63
	v_fmac_f32_e32 v60, v61, v61
	ds_bpermute_b32 v61, v57, v60
	v_cndmask_b32_e64 v64, v38, v39, s[38:39]
	s_waitcnt lgkmcnt(0)
	v_add_f32_e32 v60, v60, v61
	ds_bpermute_b32 v61, v56, v60
	s_waitcnt lgkmcnt(0)
	v_add_f32_e32 v60, v60, v61
	ds_bpermute_b32 v61, v55, v60
	s_waitcnt lgkmcnt(0)
; DI void phase_prep(const Args& a, int layer, LAS unsigned char* lds) {
;     ...
;                 for (int i = 0; i < 8; ++i) { const int tok = i * 8 + (lane >> 3), q = lane & 7;
;                     const u32x4 v = *(const u32x4*)(P + (size_t)(b * S + st * 64 + tok) * NP + srccol + q * 8);
;                     const int pos = which == 3 ? (((tok >> 4) * 2 + (q >> 2)) * 64 + (q & 3) * 16 + (tok & 15))
;                                                : ((tok >> 5) * 256 + (q >> 1) * 64 + (q & 1) * 32 + (tok & 31));
;                     *(u32x4*)(dst + pos * 8) = v;
;                     float ss = bflo(v.x) * bflo(v.x) + bfhi(v.x) * bfhi(v.x) + bflo(v.y) * bflo(v.y) + bfhi(v.y) * bfhi(v.y)
;                              + bflo(v.z) * bflo(v.z) + bfhi(v.z) * bfhi(v.z) + bflo(v.w) * bflo(v.w) + bfhi(v.w) * bfhi(v.w);
;                     ss += __shfl_xor(ss, 1); ss += __shfl_xor(ss, 2); ss += __shfl_xor(ss, 4);
;                     rmax = fmaxf(rmax, ss); }
	v_add_f32_e32 v60, v60, v61
	v_max3_f32 v66, v66, 0, v60
	v_or_b32_e32 v60, v58, v23
	v_mul_u32_u24_e32 v60, 0xd00, v60
	v_lshlrev_b32_e32 v128, 1, v60
	v_lshl_add_u64 v[60:61], v[0:1], 0, v[128:129]
	v_mov_b64_e32 v[60:61], v[78:79]
	v_mov_b64_e32 v[62:63], v[80:81]
	v_lshlrev_b32_e32 v128, 4, v64
	v_lshl_add_u64 v[64:65], v[10:11], 0, v[128:129]
	global_store_dwordx4 v[64:65], v[60:63], off
	v_lshlrev_b32_e32 v64, 16, v60
	s_nop 0
	v_and_b32_e32 v60, 0xffff0000, v60
	v_mul_f32_e32 v60, v60, v60
	v_fmac_f32_e32 v60, v64, v64
	v_lshlrev_b32_e32 v64, 16, v61
	v_fmac_f32_e32 v60, v64, v64
	v_and_b32_e32 v61, 0xffff0000, v61
	v_fmac_f32_e32 v60, v61, v61
	v_lshlrev_b32_e32 v61, 16, v62
	v_fmac_f32_e32 v60, v61, v61
	v_and_b32_e32 v61, 0xffff0000, v62
	v_fmac_f32_e32 v60, v61, v61
	v_lshlrev_b32_e32 v61, 16, v63
	v_fmac_f32_e32 v60, v61, v61
	v_and_b32_e32 v61, 0xffff0000, v63
	v_fmac_f32_e32 v60, v61, v61
	ds_bpermute_b32 v61, v57, v60
	v_cndmask_b32_e64 v64, v40, v41, s[38:39]
	s_waitcnt lgkmcnt(0)
	v_add_f32_e32 v60, v60, v61
	ds_bpermute_b32 v61, v56, v60
	s_waitcnt lgkmcnt(0)
	v_add_f32_e32 v60, v60, v61
	ds_bpermute_b32 v61, v55, v60
	s_waitcnt lgkmcnt(0)
	v_add_f32_e32 v67, v60, v61
	v_or_b32_e32 v60, v58, v24
	v_mul_u32_u24_e32 v60, 0xd00, v60
	v_lshlrev_b32_e32 v128, 1, v60
	v_lshl_add_u64 v[60:61], v[0:1], 0, v[128:129]
	v_mov_b64_e32 v[60:61], v[82:83]
	v_mov_b64_e32 v[62:63], v[84:85]
	v_lshlrev_b32_e32 v128, 4, v64
	v_lshl_add_u64 v[64:65], v[10:11], 0, v[128:129]
	global_store_dwordx4 v[64:65], v[60:63], off
	v_lshlrev_b32_e32 v64, 16, v60
	s_nop 0
	v_and_b32_e32 v60, 0xffff0000, v60
	v_mul_f32_e32 v60, v60, v60
	v_fmac_f32_e32 v60, v64, v64
	v_lshlrev_b32_e32 v64, 16, v61
	v_fmac_f32_e32 v60, v64, v64
	v_and_b32_e32 v61, 0xffff0000, v61
	v_fmac_f32_e32 v60, v61, v61
	v_lshlrev_b32_e32 v61, 16, v62
	v_fmac_f32_e32 v60, v61, v61
	v_and_b32_e32 v61, 0xffff0000, v62
	v_fmac_f32_e32 v60, v61, v61
	v_lshlrev_b32_e32 v61, 16, v63
	v_fmac_f32_e32 v60, v61, v61
	v_and_b32_e32 v61, 0xffff0000, v63
	v_mov_b64_e32 v[62:63], v[86:87]
	v_mov_b64_e32 v[64:65], v[88:89]
	v_add_co_u32_e64 v2, s[0:1], s26, v12
	v_fmac_f32_e32 v60, v61, v61
	s_nop 0
	v_addc_co_u32_e64 v3, s[0:1], 0, v13, s[0:1]
	ds_bpermute_b32 v61, v57, v60
	s_waitcnt lgkmcnt(0)
	v_add_f32_e32 v60, v60, v61
	ds_bpermute_b32 v61, v56, v60
	s_waitcnt lgkmcnt(0)
	v_add_f32_e32 v60, v60, v61
	ds_bpermute_b32 v61, v55, v60
	s_waitcnt lgkmcnt(0)
	v_add_f32_e32 v60, v60, v61
	v_max3_f32 v60, v66, v67, v60
	global_store_dwordx4 v[2:3], v[62:65], off
	v_and_b32_e32 v3, 0xffff0000, v62
	v_lshlrev_b32_e32 v2, 16, v62
	v_mul_f32_e32 v3, v3, v3
	v_fmac_f32_e32 v3, v2, v2
	v_lshlrev_b32_e32 v2, 16, v63
	v_fmac_f32_e32 v3, v2, v2
	v_and_b32_e32 v2, 0xffff0000, v63
	v_fmac_f32_e32 v3, v2, v2
	v_lshlrev_b32_e32 v2, 16, v64
	v_fmac_f32_e32 v3, v2, v2
	v_and_b32_e32 v2, 0xffff0000, v64
	v_fmac_f32_e32 v3, v2, v2
	v_lshlrev_b32_e32 v2, 16, v65
	v_fmac_f32_e32 v3, v2, v2
	v_and_b32_e32 v2, 0xffff0000, v65
	v_fmac_f32_e32 v3, v2, v2
	ds_bpermute_b32 v2, v57, v3
	s_waitcnt lgkmcnt(0)
	v_add_f32_e32 v2, v3, v2
	ds_bpermute_b32 v3, v56, v2
	s_waitcnt lgkmcnt(0)
	v_add_f32_e32 v2, v2, v3
	ds_bpermute_b32 v3, v55, v2
	s_waitcnt lgkmcnt(0)
	v_add_f32_e32 v12, v2, v3
	v_or_b32_e32 v2, v58, v26
	v_mul_u32_u24_e32 v2, 0xd00, v2
	v_lshlrev_b32_e32 v128, 1, v2
	v_lshl_add_u64 v[2:3], v[0:1], 0, v[128:129]
	v_mov_b64_e32 v[62:63], v[90:91]
	v_mov_b64_e32 v[64:65], v[92:93]
	v_or_b32_e32 v2, v59, v46
	v_lshlrev_b32_e32 v128, 4, v2
	v_lshl_add_u64 v[2:3], v[10:11], 0, v[128:129]
	v_add_co_u32_e64 v2, s[0:1], s26, v2
	s_nop 1
	v_addc_co_u32_e64 v3, s[0:1], 0, v3, s[0:1]
	global_store_dwordx4 v[2:3], v[62:65], off
	v_and_b32_e32 v3, 0xffff0000, v62
	v_lshlrev_b32_e32 v2, 16, v62
	v_mul_f32_e32 v3, v3, v3
	v_fmac_f32_e32 v3, v2, v2
	v_lshlrev_b32_e32 v2, 16, v63
	v_fmac_f32_e32 v3, v2, v2
	v_and_b32_e32 v2, 0xffff0000, v63
	v_fmac_f32_e32 v3, v2, v2
	v_lshlrev_b32_e32 v2, 16, v64
	v_fmac_f32_e32 v3, v2, v2
	v_and_b32_e32 v2, 0xffff0000, v64
	v_fmac_f32_e32 v3, v2, v2
	v_lshlrev_b32_e32 v2, 16, v65
	v_fmac_f32_e32 v3, v2, v2
	v_and_b32_e32 v2, 0xffff0000, v65
	v_fmac_f32_e32 v3, v2, v2
	ds_bpermute_b32 v2, v57, v3
	s_waitcnt lgkmcnt(0)
; DI void phase_prep(const Args& a, int layer, LAS unsigned char* lds) {
;     ...
;                 for (int i = 0; i < 8; ++i) { const int tok = i * 8 + (lane >> 3), q = lane & 7;
;                     const u32x4 v = *(const u32x4*)(P + (size_t)(b * S + st * 64 + tok) * NP + srccol + q * 8);
;                     const int pos = which == 3 ? (((tok >> 4) * 2 + (q >> 2)) * 64 + (q & 3) * 16 + (tok & 15))
;                                                : ((tok >> 5) * 256 + (q >> 1) * 64 + (q & 1) * 32 + (tok & 31));
;                     *(u32x4*)(dst + pos * 8) = v;
;                     float ss = bflo(v.x) * bflo(v.x) + bfhi(v.x) * bfhi(v.x) + bflo(v.y) * bflo(v.y) + bfhi(v.y) * bfhi(v.y)
;                              + bflo(v.z) * bflo(v.z) + bfhi(v.z) * bfhi(v.z) + bflo(v.w) * bflo(v.w) + bfhi(v.w) * bfhi(v.w);
;                     ss += __shfl_xor(ss, 1); ss += __shfl_xor(ss, 2); ss += __shfl_xor(ss, 4);
;                     rmax = fmaxf(rmax, ss); }
;                 rmax = fmaxf(rmax, __shfl_xor(rmax, 8)); rmax = fmaxf(rmax, __shfl_xor(rmax, 16)); rmax = fmaxf(rmax, __shfl_xor(rmax, 32));
;                 if (lane == 0) atomicMax((unsigned*)(ws + WS_KMAX) + (layer * 4 + (which - 3)) * 4 + bg, __builtin_bit_cast(unsigned, rmax));
	v_add_f32_e32 v2, v3, v2
	ds_bpermute_b32 v3, v56, v2
	s_waitcnt lgkmcnt(0)
	v_add_f32_e32 v2, v2, v3
	ds_bpermute_b32 v3, v55, v2
	s_waitcnt lgkmcnt(0)
	v_add_f32_e32 v2, v2, v3
	v_max3_f32 v12, v60, v12, v2
	v_or_b32_e32 v2, v58, v27
	v_mul_u32_u24_e32 v2, 0xd00, v2
	v_lshlrev_b32_e32 v128, 1, v2
	v_lshl_add_u64 v[2:3], v[0:1], 0, v[128:129]
	v_mov_b64_e32 v[60:61], v[94:95]
	v_mov_b64_e32 v[62:63], v[96:97]
	v_cndmask_b32_e64 v2, v47, v48, s[38:39]
	v_lshlrev_b32_e32 v128, 4, v2
	v_lshl_add_u64 v[2:3], v[10:11], 0, v[128:129]
	global_store_dwordx4 v[2:3], v[60:63], off
	v_and_b32_e32 v3, 0xffff0000, v60
	v_lshlrev_b32_e32 v2, 16, v60
	v_mul_f32_e32 v3, v3, v3
	v_fmac_f32_e32 v3, v2, v2
	v_lshlrev_b32_e32 v2, 16, v61
	v_fmac_f32_e32 v3, v2, v2
	v_and_b32_e32 v2, 0xffff0000, v61
	v_fmac_f32_e32 v3, v2, v2
	v_lshlrev_b32_e32 v2, 16, v62
	v_fmac_f32_e32 v3, v2, v2
	v_and_b32_e32 v2, 0xffff0000, v62
	v_fmac_f32_e32 v3, v2, v2
	v_lshlrev_b32_e32 v2, 16, v63
	v_fmac_f32_e32 v3, v2, v2
	v_and_b32_e32 v2, 0xffff0000, v63
	v_fmac_f32_e32 v3, v2, v2
	ds_bpermute_b32 v2, v57, v3
	s_waitcnt lgkmcnt(0)
	v_add_f32_e32 v2, v3, v2
	ds_bpermute_b32 v3, v56, v2
	s_waitcnt lgkmcnt(0)
	v_add_f32_e32 v2, v2, v3
	ds_bpermute_b32 v3, v55, v2
	s_waitcnt lgkmcnt(0)
	v_add_f32_e32 v13, v2, v3
	v_or_b32_e32 v2, v58, v28
	v_mul_u32_u24_e32 v2, 0xd00, v2
	v_lshlrev_b32_e32 v128, 1, v2
	v_lshl_add_u64 v[0:1], v[0:1], 0, v[128:129]
	v_mov_b64_e32 v[0:1], v[98:99]
	v_mov_b64_e32 v[2:3], v[100:101]
	v_cndmask_b32_e64 v58, v49, v50, s[38:39]
	v_lshlrev_b32_e32 v128, 4, v58
	v_lshl_add_u64 v[10:11], v[10:11], 0, v[128:129]
	global_store_dwordx4 v[10:11], v[0:3], off
	v_lshlrev_b32_e32 v10, 16, v0
	s_nop 0
	v_and_b32_e32 v0, 0xffff0000, v0
	v_mul_f32_e32 v0, v0, v0
	v_fmac_f32_e32 v0, v10, v10
	v_lshlrev_b32_e32 v10, 16, v1
	v_fmac_f32_e32 v0, v10, v10
	v_and_b32_e32 v1, 0xffff0000, v1
	v_fmac_f32_e32 v0, v1, v1
	v_lshlrev_b32_e32 v1, 16, v2
	v_fmac_f32_e32 v0, v1, v1
	v_and_b32_e32 v1, 0xffff0000, v2
	v_fmac_f32_e32 v0, v1, v1
	v_lshlrev_b32_e32 v1, 16, v3
	v_fmac_f32_e32 v0, v1, v1
	v_and_b32_e32 v1, 0xffff0000, v3
	v_fmac_f32_e32 v0, v1, v1
	ds_bpermute_b32 v1, v57, v0
	s_waitcnt lgkmcnt(0)
	v_add_f32_e32 v0, v0, v1
	ds_bpermute_b32 v1, v56, v0
	s_waitcnt lgkmcnt(0)
	v_add_f32_e32 v0, v0, v1
	ds_bpermute_b32 v1, v55, v0
	s_waitcnt lgkmcnt(0)
	v_add_f32_e32 v0, v0, v1
	v_xor_b32_e32 v1, 8, v197
	v_cmp_lt_i32_e64 s[0:1], v1, v54
	v_max3_f32 v0, v12, v13, v0
	s_nop 0
	v_cndmask_b32_e64 v1, v197, v1, s[0:1]
	v_lshlrev_b32_e32 v1, 2, v1
	ds_bpermute_b32 v1, v1, v0
	s_waitcnt lgkmcnt(0)
	v_max_f32_e32 v1, v1, v1
	v_max_f32_e32 v0, v0, v1
	v_xor_b32_e32 v1, 16, v197
	v_cmp_lt_i32_e64 s[0:1], v1, v54
	s_nop 1
	v_cndmask_b32_e64 v1, v197, v1, s[0:1]
	v_lshlrev_b32_e32 v1, 2, v1
	ds_bpermute_b32 v1, v1, v0
	s_waitcnt lgkmcnt(0)
	v_max_f32_e32 v1, v1, v1
	v_max_f32_e32 v0, v0, v1
	v_xor_b32_e32 v1, 32, v197
	v_cmp_lt_i32_e64 s[0:1], v1, v54
	s_nop 1
	v_cndmask_b32_e64 v1, v197, v1, s[0:1]
	v_lshlrev_b32_e32 v1, 2, v1
	ds_bpermute_b32 v1, v1, v0
	s_and_saveexec_b64 s[0:1], vcc
	s_cbranch_execz .LBB0_345
	v_lshrrev_b32_e32 v2, 22, v53
	v_add_u32_e32 v2, v52, v2
	v_ashrrev_i32_e32 v2, 10, v2
	s_waitcnt lgkmcnt(0)
	v_max_f32_e32 v1, v1, v1
	v_max_f32_e32 v0, v0, v0
	v_max_f32_e32 v3, v0, v1
	v_lshl_add_u32 v0, v2, 2, s8
	v_readlane_b32 s16, v252, 42
	v_ashrrev_i32_e32 v1, 31, v0
	v_readlane_b32 s17, v252, 43
	v_lshlrev_b32_e32 v128, 2, v9
	s_nop 0
	v_lshl_add_u64 v[0:1], v[0:1], 2, s[16:17]
	v_lshl_add_u64 v[0:1], v[0:1], 0, v[128:129]
	global_atomic_umax v[0:1], v3, off
	s_branch .LBB0_345
